# grid barrier: no per-XCD release word any more (non-leaders poll the cross-XCD generation word; the leader's release add is gone)
# speedup vs baseline: 1.0433x; 1.0037x over previous
.LBB0_1943:
	s_bcnt1_i32_b64 s20, s[20:21]
	v_mov_b32_e32 v0, s20
	v_readlane_b32 s20, v250, 5
	v_readlane_b32 s21, v250, 6
	s_nop 4
	s_nop 0
	s_getpc_b64 s[98:99]
